# MLA attention loop: softmax-finish VALU (exp, row-sum, bf16 pack) redistributed into QK MFMA gaps
# baseline (speedup 1.0000x reference)
; #define SBAR() __builtin_amdgcn_sched_barrier(0)
; __device__ __forceinline__ void finishSM(f32x16& p0, f32x16& p1, float alpha, float& l_reg, bf16x8& pa0, bf16x8& pa1, bf16x8& pa2, bf16x8& pa3) {
; #pragma unroll
;   for (int r = 0; r < 16; ++r) p1[r] = __builtin_amdgcn_exp2f(p1[r]);
;   float ps = 0;
; #pragma unroll
;   for (int r = 0; r < 16; ++r) ps += p0[r];
; #pragma unroll
;   for (int r = 0; r < 16; ++r) ps += p1[r];
;   { auto rr = __builtin_amdgcn_permlane32_swap(__float_as_uint(ps), __float_as_uint(ps), false, false);
;     ps = __uint_as_float(rr[0]) + __uint_as_float(rr[1]); }
;   l_reg = l_reg * alpha + ps;
;     ...
;   PK4(p0, 0, pa0); PK4(p0, 8, pa1); PK4(p1, 0, pa2); PK4(p1, 8, pa3);
;     ...
; }
; template <bool MLA>
; __device__ __forceinline__ void qkt(f32x16& p0, f32x16& p1, const char* Ks, const char* KRs, const bf16x8* qr, const char* qrl, const f32x16& negm, int r32, int hi) {
; #pragma unroll
;   for (int d0 = 0; d0 < 8; ++d0) { int cb = (d0 * 16 + hi * 8) * 2;
;     bf16x8 b0 = *reinterpret_cast<const bf16x8*>(Ks + KSWZ(r32, cb));
;     bf16x8 b1 = *reinterpret_cast<const bf16x8*>(Ks + KSWZ(32 + r32, cb));
;     if (d0 == 0) { p0 = __builtin_amdgcn_mfma_f32_32x32x16_bf16(b0, qr[0], negm, 0, 0, 0); p1 = __builtin_amdgcn_mfma_f32_32x32x16_bf16(b1, qr[0], negm, 0, 0, 0); }
;     else { p0 = __builtin_amdgcn_mfma_f32_32x32x16_bf16(b0, qr[d0], p0, 0, 0, 0); p1 = __builtin_amdgcn_mfma_f32_32x32x16_bf16(b1, qr[d0], p1, 0, 0, 0); } }
;   if constexpr (MLA) {
; #pragma unroll
;     for (int d0 = 0; d0 < 4; ++d0) { int ch = d0 * 2 + hi;
;       bf16x8 b0 = *reinterpret_cast<const bf16x8*>(KRs + KRSWZ(r32, ch));
;       bf16x8 b1 = *reinterpret_cast<const bf16x8*>(KRs + KRSWZ(32 + r32, ch));
;       const bf16x8 qq = *reinterpret_cast<const bf16x8*>(qrl + d0 * 1024);
;       p0 = __builtin_amdgcn_mfma_f32_32x32x16_bf16(b0, qq, p0, 0, 0, 0);
;       p1 = __builtin_amdgcn_mfma_f32_32x32x16_bf16(b1, qq, p1, 0, 0, 0); }
;   }
; }
; template <bool MLA> ...
;     ...
;     SBAR(); DMA_TILE(j + 1, s_next); SBAR();
;     qkt<MLA>(pB0, pB1, K_lds + s_cur * SHM_K, KR_lds + s_cur * SHM_KR, qr, qrl, negm, r32, hi);
;     finishSM(pA0, pA1, alA, l_reg, pa0, pa1, pa2, pa3);
.LBB0_101:
	s_mov_b32 s10, s24
	s_mov_b32 s24, s35
	s_lshl_b32 s2, s25, 14
	s_add_i32 s27, s2, 0
	s_add_i32 s32, s27, s15
	s_lshl_b32 s30, s25, 13
	s_lshl_b32 s11, s10, 14
	s_add_i32 s3, s11, 0
	v_add_u32_e32 v0, s3, v210
	ds_read_b128 v[234:237], v0 offset:57344
	ds_read_b128 v[98:101], v0 offset:49152
	v_add_u32_e32 v0, s3, v209
	s_lshl_b32 s2, s10, 13
	s_add_i32 s2, s2, 0
	s_add_i32 s2, s2, 0x18000
	s_add_u32 vcc_lo, s28, s46
	s_addc_u32 vcc_hi, s29, s47
	s_add_i32 m0, s32, 0xc000
	v_lshl_add_u64 v[250:251], v[172:173], 0, vcc
	global_load_lds_dwordx4 v[250:251], off
	v_exp_f32_e32 v213, v82
	v_add_f32_e32 v212, 0, v227
	v_add_f32_e32 v212, v229, v212
	s_waitcnt lgkmcnt(0)
	v_mfma_f32_32x32x16_bf16 v[114:129], v[98:101], v[158:161], v[66:81]
	v_exp_f32_e32 v246, v83
	v_add_f32_e32 v212, v225, v212
	v_add_f32_e32 v212, v228, v212
	s_lshl_b32 s31, s35, 14
	v_mfma_f32_32x32x16_bf16 v[98:113], v[234:237], v[158:161], v[66:81]
	ds_read_b128 v[234:237], v0 offset:57344
	ds_read_b128 v[238:241], v0 offset:49152
	v_add_u32_e32 v0, s3, v208
	s_add_u32 vcc_lo, s28, 0x4380100
	s_addc_u32 vcc_hi, s29, 0
	s_mov_b32 m0, s32
	v_lshl_add_u64 v[250:251], v[170:171], 0, vcc
	global_load_lds_dwordx4 v[250:251], off
	v_exp_f32_e32 v247, v84
	v_add_f32_e32 v212, v224, v212
	v_add_f32_e32 v212, v226, v212
	s_waitcnt lgkmcnt(0)
	v_mfma_f32_32x32x16_bf16 v[114:129], v[238:241], v[154:157], v[114:129]
	v_exp_f32_e32 v249, v85
	v_add_f32_e32 v212, v222, v212
	v_add_f32_e32 v212, v223, v212
	v_mfma_f32_32x32x16_bf16 v[98:113], v[234:237], v[154:157], v[98:113]
	ds_read_b128 v[234:237], v0 offset:57344
	ds_read_b128 v[238:241], v0 offset:49152
	v_add_u32_e32 v0, s3, v207
	s_add_u32 vcc_lo, s28, s46
	s_addc_u32 vcc_hi, s29, s47
	s_add_i32 m0, s32, 0xc400
	v_lshl_add_u64 v[250:251], v[174:175], 0, vcc
	global_load_lds_dwordx4 v[250:251], off
	v_exp_f32_e32 v252, v86
	v_add_f32_e32 v212, v219, v212
	v_add_f32_e32 v212, v221, v212
	s_waitcnt lgkmcnt(0)
	v_mfma_f32_32x32x16_bf16 v[114:129], v[238:241], v[150:153], v[114:129]
	v_exp_f32_e32 v253, v87
	v_add_f32_e32 v212, v218, v212
	v_add_f32_e32 v212, v220, v212
	v_mfma_f32_32x32x16_bf16 v[98:113], v[234:237], v[150:153], v[98:113]
	ds_read_b128 v[234:237], v0 offset:57344
	ds_read_b128 v[238:241], v0 offset:49152
	v_add_u32_e32 v0, s3, v206
	s_add_u32 vcc_lo, s28, 0x4380180
	s_addc_u32 vcc_hi, s29, 0
	s_add_i32 m0, s32, 0x400
	v_lshl_add_u64 v[250:251], v[170:171], 0, vcc
	global_load_lds_dwordx4 v[250:251], off
	v_exp_f32_e32 v254, v88
	v_add_f32_e32 v212, v215, v212
	v_add_f32_e32 v212, v217, v212
	s_waitcnt lgkmcnt(0)
	v_mfma_f32_32x32x16_bf16 v[114:129], v[238:241], v[146:149], v[114:129]
	v_exp_f32_e32 v255, v89
	v_add_f32_e32 v212, v214, v212
	v_add_f32_e32 v212, v216, v212
	v_mfma_f32_32x32x16_bf16 v[98:113], v[234:237], v[146:149], v[98:113]
	ds_read_b128 v[234:237], v0 offset:57344
	ds_read_b128 v[238:241], v0 offset:49152
	v_add_u32_e32 v0, s3, v205
	s_add_u32 vcc_lo, s28, 0x2e340600
	s_addc_u32 vcc_hi, s29, 0
	s_add_i32 m0, s23, s30
	v_lshl_add_u64 v[250:251], v[168:169], 0, vcc
	global_load_lds_dwordx4 v[250:251], off
	v_cvt_pk_bf16_f32 v82, v227, v229
	v_exp_f32_e32 v90, v90
	v_cvt_pk_bf16_f32 v83, v225, v228
	s_waitcnt lgkmcnt(0)
	v_mfma_f32_32x32x16_bf16 v[114:129], v[238:241], v[142:145], v[114:129]
	v_exp_f32_e32 v91, v91
	v_cvt_pk_bf16_f32 v84, v224, v226
	v_exp_f32_e32 v92, v92
	v_mfma_f32_32x32x16_bf16 v[98:113], v[234:237], v[142:145], v[98:113]
	ds_read_b128 v[234:237], v0 offset:57344
	ds_read_b128 v[238:241], v0 offset:49152
	v_add_u32_e32 v0, s3, v204
	v_cvt_pk_bf16_f32 v85, v222, v223
	v_exp_f32_e32 v93, v93
	v_cvt_pk_bf16_f32 v86, v219, v221
	s_waitcnt lgkmcnt(0)
	v_mfma_f32_32x32x16_bf16 v[114:129], v[238:241], v[138:141], v[114:129]
	v_exp_f32_e32 v94, v94
	v_cvt_pk_bf16_f32 v87, v218, v220
	v_exp_f32_e32 v95, v95
	v_mfma_f32_32x32x16_bf16 v[98:113], v[234:237], v[138:141], v[98:113]
	ds_read_b128 v[234:237], v0 offset:57344
	ds_read_b128 v[238:241], v0 offset:49152
	v_add_u32_e32 v0, s3, v203
	v_cvt_pk_bf16_f32 v88, v215, v217
	v_exp_f32_e32 v96, v96
	v_cvt_pk_bf16_f32 v89, v214, v216
	s_waitcnt lgkmcnt(0)
	v_mfma_f32_32x32x16_bf16 v[114:129], v[238:241], v[134:137], v[114:129]
	v_exp_f32_e32 v97, v97
	v_add_f32_e32 v212, v213, v212
	v_add_f32_e32 v212, v246, v212
	v_mfma_f32_32x32x16_bf16 v[98:113], v[234:237], v[134:137], v[98:113]
	ds_read_b128 v[234:237], v0 offset:57344
	ds_read_b128 v[238:241], v0 offset:49152
	v_add_u32_e32 v0, s2, v200
	v_add_f32_e32 v212, v247, v212
	v_add_f32_e32 v212, v249, v212
	v_add_f32_e32 v212, v252, v212
	s_waitcnt lgkmcnt(0)
	v_mfma_f32_32x32x16_bf16 v[114:129], v[238:241], v[130:133], v[114:129]
	v_add_f32_e32 v212, v253, v212
	v_add_f32_e32 v212, v254, v212
	v_add_f32_e32 v212, v255, v212
	v_mfma_f32_32x32x16_bf16 v[98:113], v[234:237], v[130:133], v[98:113]
	ds_read_b128 v[234:237], v0
	ds_read_b128 v[238:241], v0 offset:4096
	ds_read_b128 v[242:245], v198
	v_add_u32_e32 v0, s2, v201
	v_add_f32_e32 v212, v90, v212
	v_add_f32_e32 v212, v91, v212
	s_waitcnt lgkmcnt(0)
	v_mfma_f32_32x32x16_bf16 v[114:129], v[234:237], v[242:245], v[114:129]
	v_add_f32_e32 v212, v92, v212
	v_add_f32_e32 v212, v93, v212
	v_mfma_f32_32x32x16_bf16 v[98:113], v[238:241], v[242:245], v[98:113]
	ds_read_b128 v[234:237], v0
	ds_read_b128 v[238:241], v0 offset:4096
	ds_read_b128 v[242:245], v198 offset:1024
	v_add_u32_e32 v0, s2, v199
	v_add_f32_e32 v212, v94, v212
	v_add_f32_e32 v212, v95, v212
	s_waitcnt lgkmcnt(0)
; template <bool FIRST, bool MLA>
; __device__ __forceinline__ void partialSM(f32x16& p0, f32x16& p1, f32x16& negm, float& m_reg, float& alpha) {
;   float a = max3f(p0[0], p0[1], p1[0]), b = max3f(p0[2], p0[3], p1[1]); a = max3f(a, p1[2], p1[3]);
; #pragma unroll
;   for (int r = 4; r < 16; r += 4) { a = max3f(a, p0[r], p0[r + 1]); b = max3f(b, p0[r + 2], p0[r + 3]); a = max3f(a, p1[r], p1[r + 1]); b = max3f(b, p1[r + 2], p1[r + 3]); }
;   float pmax = fmaxf(a, b);
;   { auto rr = __builtin_amdgcn_permlane32_swap(__float_as_uint(pmax), __float_as_uint(pmax), false, false);
;     pmax = fmaxf(__uint_as_float(rr[0]), __uint_as_float(rr[1])); }
;   alpha = 1.f;
;   if constexpr (MLA) {
;     if (FIRST) m_reg = pmax;
;     else if (!__builtin_expect(__all(pmax - m_reg <= THR2), 1)) { const float mn = fmaxf(m_reg, pmax); alpha = __builtin_amdgcn_exp2f(m_reg - mn); m_reg = mn; }
; #pragma unroll
;     for (int r = 0; r < 16; ++r) { p0[r] -= m_reg; p1[r] -= m_reg; }
;   } else
;   if (FIRST || __builtin_expect(__any(pmax > THR2), 0)) {
;     const float d = FIRST ? pmax : fmaxf(pmax, 0.f);
; #pragma unroll
;     for (int r = 0; r < 16; ++r) { p0[r] -= d; p1[r] -= d; }
; #pragma unroll
;     for (int r = 0; r < 16; ++r) negm[r] -= d;
;     asm volatile("" : "+v"(negm));
;     if (!FIRST) alpha = __builtin_amdgcn_exp2f(-d);
;   }
; #pragma unroll
;   for (int r = 0; r < 16; ++r) p0[r] = __builtin_amdgcn_exp2f(p0[r]);
; }
; __device__ __forceinline__ void finishSM(f32x16& p0, f32x16& p1, float alpha, float& l_reg, bf16x8& pa0, bf16x8& pa1, bf16x8& pa2, bf16x8& pa3) {
; #pragma unroll
;   for (int r = 0; r < 16; ++r) p1[r] = __builtin_amdgcn_exp2f(p1[r]);
;   float ps = 0;
; #pragma unroll
;   for (int r = 0; r < 16; ++r) ps += p0[r];
; #pragma unroll
;   for (int r = 0; r < 16; ++r) ps += p1[r];
;   { auto rr = __builtin_amdgcn_permlane32_swap(__float_as_uint(ps), __float_as_uint(ps), false, false);
;     ps = __uint_as_float(rr[0]) + __uint_as_float(rr[1]); }
;   l_reg = l_reg * alpha + ps;
;     ...
;   PK4(p0, 0, pa0); PK4(p0, 8, pa1); PK4(p1, 0, pa2); PK4(p1, 8, pa3);
;     ...
; }
; template <int D0> __device__ __forceinline__ void pv_one(f32x16& od, int vb, bf16x8 pa0, bf16x8 pa1, bf16x8 pa2, bf16x8 pa3) {
;   const s16x4 l0 = tr_read<v_rd_off(D0, 0, 0)>(vb), h0 = tr_read<v_rd_off(D0, 0, 1)>(vb), l1 = tr_read<v_rd_off(D0, 1, 0)>(vb), h1 = tr_read<v_rd_off(D0, 1, 1)>(vb);
	v_mfma_f32_32x32x16_bf16 v[114:129], v[234:237], v[242:245], v[114:129]
	v_add_f32_e32 v212, v96, v212
	v_add_f32_e32 v212, v97, v212
	v_mfma_f32_32x32x16_bf16 v[98:113], v[238:241], v[242:245], v[98:113]
	ds_read_b128 v[234:237], v0
	ds_read_b128 v[238:241], v0 offset:4096
	ds_read_b128 v[242:245], v198 offset:2048
	v_add_u32_e32 v0, s2, v202
	v_cvt_pk_bf16_f32 v97, v96, v97
	v_cvt_pk_bf16_f32 v96, v94, v95
	s_waitcnt lgkmcnt(0)
	v_mfma_f32_32x32x16_bf16 v[114:129], v[234:237], v[242:245], v[114:129]
	v_cvt_pk_bf16_f32 v95, v92, v93
	v_cvt_pk_bf16_f32 v94, v90, v91
	v_mfma_f32_32x32x16_bf16 v[98:113], v[238:241], v[242:245], v[98:113]
	ds_read_b128 v[234:237], v0
	ds_read_b128 v[238:241], v0 offset:4096
	ds_read_b128 v[242:245], v198 offset:3072
	v_cvt_pk_bf16_f32 v90, v213, v246
	v_cvt_pk_bf16_f32 v91, v247, v249
	s_waitcnt lgkmcnt(0)
	v_mfma_f32_32x32x16_bf16 v[114:129], v[234:237], v[242:245], v[114:129]
	v_cvt_pk_bf16_f32 v92, v252, v253
	v_cvt_pk_bf16_f32 v93, v254, v255
	v_mfma_f32_32x32x16_bf16 v[98:113], v[238:241], v[242:245], v[98:113]
	v_add_u32_e32 v213, s31, v197
	ds_read_b64_tr_b16 v[214:215], v213 offset:0
	ds_read_b64_tr_b16 v[216:217], v213 offset:0x800
	ds_read_b64_tr_b16 v[218:219], v213 offset:0x1000
	ds_read_b64_tr_b16 v[220:221], v213 offset:0x1800
	ds_read_b64_tr_b16 v[222:223], v213 offset:0x2000
	ds_read_b64_tr_b16 v[224:225], v213 offset:0x2800
	ds_read_b64_tr_b16 v[226:227], v213 offset:0x3000
	ds_read_b64_tr_b16 v[228:229], v213 offset:0x3800
	s_waitcnt lgkmcnt(0)
	v_mov_b32_e32 v0, v212
	s_nop 1
	v_permlane32_swap_b32_e32 v0, v212
	v_permlane32_swap_b32_e32 v82, v84
	v_permlane32_swap_b32_e32 v83, v85
	v_permlane32_swap_b32_e32 v86, v88
	v_permlane32_swap_b32_e32 v87, v89
	v_permlane32_swap_b32_e32 v90, v92
	v_permlane32_swap_b32_e32 v91, v93
	v_permlane32_swap_b32_e32 v94, v96
	v_permlane32_swap_b32_e32 v95, v97
	v_mfma_f32_32x32x16_bf16 v[50:65], v[82:85], v[214:217], v[50:65]
	ds_read_b64_tr_b16 v[214:215], v213 offset:0x200
	ds_read_b64_tr_b16 v[216:217], v213 offset:0xa00
	v_mfma_f32_32x32x16_bf16 v[50:65], v[86:89], v[218:221], v[50:65]
	ds_read_b64_tr_b16 v[218:219], v213 offset:0x1200
	ds_read_b64_tr_b16 v[220:221], v213 offset:0x1a00
	v_mfma_f32_32x32x16_bf16 v[50:65], v[90:93], v[222:225], v[50:65]
	ds_read_b64_tr_b16 v[222:223], v213 offset:0x2200
	ds_read_b64_tr_b16 v[224:225], v213 offset:0x2a00
	v_mfma_f32_32x32x16_bf16 v[50:65], v[94:97], v[226:229], v[50:65]
	ds_read_b64_tr_b16 v[226:227], v213 offset:0x3200
	ds_read_b64_tr_b16 v[228:229], v213 offset:0x3a00
	s_waitcnt lgkmcnt(0)
	v_mfma_f32_32x32x16_bf16 v[34:49], v[82:85], v[214:217], v[34:49]
	ds_read_b64_tr_b16 v[214:215], v213 offset:0x400
	ds_read_b64_tr_b16 v[216:217], v213 offset:0xc00
	v_mfma_f32_32x32x16_bf16 v[34:49], v[86:89], v[218:221], v[34:49]
	ds_read_b64_tr_b16 v[218:219], v213 offset:0x1400
	ds_read_b64_tr_b16 v[220:221], v213 offset:0x1c00
	v_mfma_f32_32x32x16_bf16 v[34:49], v[90:93], v[222:225], v[34:49]
	ds_read_b64_tr_b16 v[222:223], v213 offset:0x2400
	ds_read_b64_tr_b16 v[224:225], v213 offset:0x2c00
	v_mfma_f32_32x32x16_bf16 v[34:49], v[94:97], v[226:229], v[34:49]
	ds_read_b64_tr_b16 v[226:227], v213 offset:0x3400
	ds_read_b64_tr_b16 v[228:229], v213 offset:0x3c00
	s_waitcnt lgkmcnt(0)
	v_mfma_f32_32x32x16_bf16 v[18:33], v[82:85], v[214:217], v[18:33]
	ds_read_b64_tr_b16 v[214:215], v213 offset:0x600
	ds_read_b64_tr_b16 v[216:217], v213 offset:0xe00
	v_mfma_f32_32x32x16_bf16 v[18:33], v[86:89], v[218:221], v[18:33]
	ds_read_b64_tr_b16 v[218:219], v213 offset:0x1600
	ds_read_b64_tr_b16 v[220:221], v213 offset:0x1e00
	v_mfma_f32_32x32x16_bf16 v[18:33], v[90:93], v[222:225], v[18:33]
	ds_read_b64_tr_b16 v[222:223], v213 offset:0x2600
	ds_read_b64_tr_b16 v[224:225], v213 offset:0x2e00
	v_mfma_f32_32x32x16_bf16 v[18:33], v[94:97], v[226:229], v[18:33]
	ds_read_b64_tr_b16 v[226:227], v213 offset:0x3600
	ds_read_b64_tr_b16 v[228:229], v213 offset:0x3e00
	s_waitcnt lgkmcnt(0)
	v_mfma_f32_32x32x16_bf16 v[2:17], v[82:85], v[214:217], v[2:17]
	v_max_f32_e32 v82, v115, v115
	v_max_f32_e32 v83, v114, v114
	v_max_f32_e32 v82, v83, v82
	v_max3_f32 v83, v116, v117, v99
	v_max3_f32 v82, v82, v98, v100
	v_max3_f32 v82, v82, v101, v118
	v_max3_f32 v83, v83, v120, v121
	v_mfma_f32_32x32x16_bf16 v[2:17], v[86:89], v[218:221], v[2:17]
	v_max3_f32 v82, v82, v119, v102
	v_max3_f32 v83, v83, v104, v105
	v_max3_f32 v82, v82, v103, v122
	v_max3_f32 v83, v83, v124, v125
	v_max3_f32 v82, v82, v123, v106
	v_max3_f32 v83, v83, v108, v109
	v_max3_f32 v82, v82, v107, v126
	v_mfma_f32_32x32x16_bf16 v[2:17], v[90:93], v[222:225], v[2:17]
	v_max3_f32 v83, v83, v128, v129
	v_max3_f32 v82, v82, v127, v110
	v_max3_f32 v83, v83, v112, v113
	v_max3_f32 v82, v82, v111, v83
	v_mov_b32_e32 v83, v82
	s_nop 1
	v_permlane32_swap_b32_e32 v82, v83
	v_mfma_f32_32x32x16_bf16 v[2:17], v[94:97], v[226:229], v[2:17]
	v_max_f32_e32 v83, v83, v83
	v_max_f32_e32 v82, v82, v82
	v_max_f32_e32 v82, v82, v83
	v_cmp_lt_f32_e32 vcc, s40, v82
	s_cbranch_vccnz .LBB0_113
	v_mov_b32_e32 v213, 1.0
	v_cmp_gt_f32_e32 vcc, 1.0, v213
	s_cbranch_vccz .LBB0_106

; template <bool FIRST, bool MLA>
; __device__ __forceinline__ void partialSM(f32x16& p0, f32x16& p1, f32x16& negm, float& m_reg, float& alpha) {
;     ...
;   for (int r = 0; r < 16; ++r) p0[r] = __builtin_amdgcn_exp2f(p0[r]);
; }
; __device__ __forceinline__ void finishSM(f32x16& p0, f32x16& p1, float alpha, float& l_reg, bf16x8& pa0, bf16x8& pa1, bf16x8& pa2, bf16x8& pa3) {
; #pragma unroll
;   for (int r = 0; r < 16; ++r) p1[r] = __builtin_amdgcn_exp2f(p1[r]);
;   float ps = 0;
; #pragma unroll
;   for (int r = 0; r < 16; ++r) ps += p0[r];
; #pragma unroll
;   for (int r = 0; r < 16; ++r) ps += p1[r];
;   { auto rr = __builtin_amdgcn_permlane32_swap(__float_as_uint(ps), __float_as_uint(ps), false, false);
;     ps = __uint_as_float(rr[0]) + __uint_as_float(rr[1]); }
;   l_reg = l_reg * alpha + ps;
;     ...
;   PK4(p0, 0, pa0); PK4(p0, 8, pa1); PK4(p1, 0, pa2); PK4(p1, 8, pa3);
;     ...
; }
; template <bool MLA>
; __device__ __forceinline__ void qkt(f32x16& p0, f32x16& p1, const char* Ks, const char* KRs, const bf16x8* qr, const char* qrl, const f32x16& negm, int r32, int hi) {
; #pragma unroll
;   for (int d0 = 0; d0 < 8; ++d0) { int cb = (d0 * 16 + hi * 8) * 2;
;     bf16x8 b0 = *reinterpret_cast<const bf16x8*>(Ks + KSWZ(r32, cb));
;     bf16x8 b1 = *reinterpret_cast<const bf16x8*>(Ks + KSWZ(32 + r32, cb));
;     if (d0 == 0) { p0 = __builtin_amdgcn_mfma_f32_32x32x16_bf16(b0, qr[0], negm, 0, 0, 0); p1 = __builtin_amdgcn_mfma_f32_32x32x16_bf16(b1, qr[0], negm, 0, 0, 0); }
;     else { p0 = __builtin_amdgcn_mfma_f32_32x32x16_bf16(b0, qr[d0], p0, 0, 0, 0); p1 = __builtin_amdgcn_mfma_f32_32x32x16_bf16(b1, qr[d0], p1, 0, 0, 0); } }
;   if constexpr (MLA) {
; #pragma unroll
;     for (int d0 = 0; d0 < 4; ++d0) { int ch = d0 * 2 + hi;
;       bf16x8 b0 = *reinterpret_cast<const bf16x8*>(KRs + KRSWZ(r32, ch));
;       bf16x8 b1 = *reinterpret_cast<const bf16x8*>(KRs + KRSWZ(32 + r32, ch));
;       const bf16x8 qq = *reinterpret_cast<const bf16x8*>(qrl + d0 * 1024);
;       p0 = __builtin_amdgcn_mfma_f32_32x32x16_bf16(b0, qq, p0, 0, 0, 0);
;       p1 = __builtin_amdgcn_mfma_f32_32x32x16_bf16(b1, qq, p1, 0, 0, 0); }
;   }
; }
; template <bool MLA> ...
;     ...
;     RESC(alB); WAIT_BAR(); ROT();
;     SBAR(); DMA_TILE(j + 2, s_next); SBAR();
;     qkt<MLA>(pA0, pA1, K_lds + s_cur * SHM_K, KR_lds + s_cur * SHM_KR, qr, qrl, negm, r32, hi);
;     finishSM(pB0, pB1, alB, l_reg, pa0, pa1, pa2, pa3);
.LBB0_106:
	s_waitcnt vmcnt(0)
	v_exp_f32_e32 v218, v114
	v_exp_f32_e32 v219, v115
	v_exp_f32_e32 v220, v116
	v_exp_f32_e32 v221, v117
	v_exp_f32_e32 v222, v118
	v_exp_f32_e32 v223, v119
	v_exp_f32_e32 v224, v120
	v_exp_f32_e32 v225, v121
	v_exp_f32_e32 v226, v122
	v_exp_f32_e32 v227, v123
	v_exp_f32_e32 v228, v124
	v_exp_f32_e32 v229, v125
	v_exp_f32_e32 v234, v126
	v_exp_f32_e32 v235, v127
	v_exp_f32_e32 v236, v128
	v_exp_f32_e32 v237, v129
	s_waitcnt vmcnt(0)
	s_barrier
	s_add_i32 s31, s19, s31
	v_add_u32_e32 v82, s27, v210
	ds_read_b128 v[176:179], v82 offset:57344
	ds_read_b128 v[82:85], v82 offset:49152
	v_add_u32_e32 v180, s27, v209
	s_add_i32 s2, s30, 0
	s_add_i32 s2, s2, 0x18000
	s_add_u32 vcc_lo, s28, s48
	s_addc_u32 vcc_hi, s29, s49
	s_add_i32 m0, s31, 0xc000
	v_lshl_add_u64 v[250:251], v[172:173], 0, vcc
	global_load_lds_dwordx4 v[250:251], off
	v_exp_f32_e32 v238, v100
	v_add_f32_e32 v255, 0, v218
	v_add_f32_e32 v255, v219, v255
	s_waitcnt lgkmcnt(0)
	v_mfma_f32_32x32x16_bf16 v[114:129], v[82:85], v[158:161], v[66:81]
	v_exp_f32_e32 v239, v101
	v_add_f32_e32 v255, v220, v255
	v_add_f32_e32 v255, v221, v255
	v_mfma_f32_32x32x16_bf16 v[82:97], v[176:179], v[158:161], v[66:81]
	ds_read_b128 v[176:179], v180 offset:57344
	ds_read_b128 v[180:183], v180 offset:49152
	s_add_u32 vcc_lo, s28, 0x43c0100
	s_addc_u32 vcc_hi, s29, 0
	s_mov_b32 m0, s31
	v_lshl_add_u64 v[250:251], v[170:171], 0, vcc
	global_load_lds_dwordx4 v[250:251], off
	v_exp_f32_e32 v246, v102
	v_add_f32_e32 v255, v222, v255
	v_add_f32_e32 v255, v223, v255
	s_waitcnt lgkmcnt(0)
	v_mfma_f32_32x32x16_bf16 v[114:129], v[180:183], v[154:157], v[114:129]
	v_exp_f32_e32 v247, v103
	v_add_f32_e32 v255, v224, v255
	v_add_f32_e32 v255, v225, v255
	v_add_u32_e32 v180, s27, v208
	v_mfma_f32_32x32x16_bf16 v[82:97], v[176:179], v[154:157], v[82:97]
	ds_read_b128 v[176:179], v180 offset:57344
	ds_read_b128 v[180:183], v180 offset:49152
	s_add_u32 vcc_lo, s28, s48
	s_addc_u32 vcc_hi, s29, s49
	s_add_i32 m0, s31, 0xc400
	v_lshl_add_u64 v[250:251], v[174:175], 0, vcc
	global_load_lds_dwordx4 v[250:251], off
	v_exp_f32_e32 v249, v104
	v_add_f32_e32 v255, v226, v255
	v_add_f32_e32 v255, v227, v255
	s_waitcnt lgkmcnt(0)
	v_mfma_f32_32x32x16_bf16 v[114:129], v[180:183], v[150:153], v[114:129]
	v_exp_f32_e32 v252, v105
	v_add_f32_e32 v255, v228, v255
	v_add_f32_e32 v255, v229, v255
	v_add_u32_e32 v180, s27, v207
	v_mfma_f32_32x32x16_bf16 v[82:97], v[176:179], v[150:153], v[82:97]
	ds_read_b128 v[176:179], v180 offset:57344
	ds_read_b128 v[180:183], v180 offset:49152
	s_add_u32 vcc_lo, s28, 0x43c0180
	s_addc_u32 vcc_hi, s29, 0
	s_add_i32 m0, s31, 0x400
	v_lshl_add_u64 v[250:251], v[170:171], 0, vcc
	global_load_lds_dwordx4 v[250:251], off
	v_exp_f32_e32 v253, v106
	v_add_f32_e32 v255, v234, v255
	v_add_f32_e32 v255, v235, v255
	s_waitcnt lgkmcnt(0)
	v_mfma_f32_32x32x16_bf16 v[114:129], v[180:183], v[146:149], v[114:129]
	v_exp_f32_e32 v254, v107
	v_add_f32_e32 v255, v236, v255
	v_add_f32_e32 v255, v237, v255
	v_add_u32_e32 v180, s27, v206
	v_mfma_f32_32x32x16_bf16 v[82:97], v[176:179], v[146:149], v[82:97]
	ds_read_b128 v[176:179], v180 offset:57344
	ds_read_b128 v[180:183], v180 offset:49152
	s_lshl_b32 s32, s24, 13
	s_add_u32 vcc_lo, s28, 0x2e360600
	s_addc_u32 vcc_hi, s29, 0
	s_add_i32 m0, s23, s32
	v_lshl_add_u64 v[250:251], v[168:169], 0, vcc
	global_load_lds_dwordx4 v[250:251], off
	v_cvt_pk_bf16_f32 v100, v218, v219
	v_exp_f32_e32 v98, v98
	s_waitcnt lgkmcnt(0)
	v_mfma_f32_32x32x16_bf16 v[114:129], v[180:183], v[142:145], v[114:129]
	v_cvt_pk_bf16_f32 v101, v220, v221
	v_exp_f32_e32 v99, v99
	v_add_u32_e32 v180, s27, v205
	v_mfma_f32_32x32x16_bf16 v[82:97], v[176:179], v[142:145], v[82:97]
	ds_read_b128 v[176:179], v180 offset:57344
	ds_read_b128 v[180:183], v180 offset:49152
	v_cvt_pk_bf16_f32 v102, v222, v223
	v_exp_f32_e32 v108, v108
	s_waitcnt lgkmcnt(0)
	v_mfma_f32_32x32x16_bf16 v[114:129], v[180:183], v[138:141], v[114:129]
	v_cvt_pk_bf16_f32 v103, v224, v225
	v_exp_f32_e32 v109, v109
	v_add_u32_e32 v180, s27, v204
	v_mfma_f32_32x32x16_bf16 v[82:97], v[176:179], v[138:141], v[82:97]
	ds_read_b128 v[176:179], v180 offset:57344
	ds_read_b128 v[180:183], v180 offset:49152
	v_cvt_pk_bf16_f32 v104, v226, v227
	v_exp_f32_e32 v110, v110
	s_waitcnt lgkmcnt(0)
	v_mfma_f32_32x32x16_bf16 v[114:129], v[180:183], v[134:137], v[114:129]
	v_cvt_pk_bf16_f32 v105, v228, v229
	v_exp_f32_e32 v111, v111
	v_add_u32_e32 v180, s27, v203
	v_mfma_f32_32x32x16_bf16 v[82:97], v[176:179], v[134:137], v[82:97]
	ds_read_b128 v[176:179], v180 offset:57344
	ds_read_b128 v[180:183], v180 offset:49152
	v_cvt_pk_bf16_f32 v106, v234, v235
	v_exp_f32_e32 v112, v112
	s_waitcnt lgkmcnt(0)
	v_mfma_f32_32x32x16_bf16 v[114:129], v[180:183], v[130:133], v[114:129]
	v_cvt_pk_bf16_f32 v107, v236, v237
	v_exp_f32_e32 v113, v113
	v_add_u32_e32 v180, s2, v200
	v_mfma_f32_32x32x16_bf16 v[82:97], v[176:179], v[130:133], v[82:97]
	ds_read_b128 v[176:179], v180
	ds_read_b128 v[180:183], v180 offset:4096
	ds_read_b128 v[214:217], v198
	v_add_f32_e32 v255, v98, v255
	v_add_f32_e32 v255, v99, v255
	s_waitcnt lgkmcnt(0)
	v_mfma_f32_32x32x16_bf16 v[114:129], v[176:179], v[214:217], v[114:129]
	v_add_f32_e32 v255, v238, v255
	v_add_f32_e32 v255, v239, v255
	v_mfma_f32_32x32x16_bf16 v[82:97], v[180:183], v[214:217], v[82:97]
	v_add_u32_e32 v180, s2, v201
	ds_read_b128 v[176:179], v180
	ds_read_b128 v[180:183], v180 offset:4096
	ds_read_b128 v[214:217], v198 offset:1024
	v_add_f32_e32 v255, v246, v255
	v_add_f32_e32 v255, v247, v255
	s_waitcnt lgkmcnt(0)
; template <bool FIRST, bool MLA>
; __device__ __forceinline__ void partialSM(f32x16& p0, f32x16& p1, f32x16& negm, float& m_reg, float& alpha) {
;   float a = max3f(p0[0], p0[1], p1[0]), b = max3f(p0[2], p0[3], p1[1]); a = max3f(a, p1[2], p1[3]);
; #pragma unroll
;   for (int r = 4; r < 16; r += 4) { a = max3f(a, p0[r], p0[r + 1]); b = max3f(b, p0[r + 2], p0[r + 3]); a = max3f(a, p1[r], p1[r + 1]); b = max3f(b, p1[r + 2], p1[r + 3]); }
;   float pmax = fmaxf(a, b);
;   { auto rr = __builtin_amdgcn_permlane32_swap(__float_as_uint(pmax), __float_as_uint(pmax), false, false);
;     pmax = fmaxf(__uint_as_float(rr[0]), __uint_as_float(rr[1])); }
;   alpha = 1.f;
;   if constexpr (MLA) {
;     if (FIRST) m_reg = pmax;
;     else if (!__builtin_expect(__all(pmax - m_reg <= THR2), 1)) { const float mn = fmaxf(m_reg, pmax); alpha = __builtin_amdgcn_exp2f(m_reg - mn); m_reg = mn; }
; #pragma unroll
;     for (int r = 0; r < 16; ++r) { p0[r] -= m_reg; p1[r] -= m_reg; }
;   } else
;   if (FIRST || __builtin_expect(__any(pmax > THR2), 0)) {
;     const float d = FIRST ? pmax : fmaxf(pmax, 0.f);
; #pragma unroll
;     for (int r = 0; r < 16; ++r) { p0[r] -= d; p1[r] -= d; }
; #pragma unroll
;     for (int r = 0; r < 16; ++r) negm[r] -= d;
;     asm volatile("" : "+v"(negm));
;     if (!FIRST) alpha = __builtin_amdgcn_exp2f(-d);
;   }
; #pragma unroll
;   for (int r = 0; r < 16; ++r) p0[r] = __builtin_amdgcn_exp2f(p0[r]);
; }
; __device__ __forceinline__ void finishSM(f32x16& p0, f32x16& p1, float alpha, float& l_reg, bf16x8& pa0, bf16x8& pa1, bf16x8& pa2, bf16x8& pa3) {
; #pragma unroll
;   for (int r = 0; r < 16; ++r) p1[r] = __builtin_amdgcn_exp2f(p1[r]);
;   float ps = 0;
; #pragma unroll
;   for (int r = 0; r < 16; ++r) ps += p0[r];
; #pragma unroll
;   for (int r = 0; r < 16; ++r) ps += p1[r];
;   { auto rr = __builtin_amdgcn_permlane32_swap(__float_as_uint(ps), __float_as_uint(ps), false, false);
;     ps = __uint_as_float(rr[0]) + __uint_as_float(rr[1]); }
;   l_reg = l_reg * alpha + ps;
;     ...
;   PK4(p0, 0, pa0); PK4(p0, 8, pa1); PK4(p1, 0, pa2); PK4(p1, 8, pa3);
;     ...
; }
; template <int D0> __device__ __forceinline__ void pv_one(f32x16& od, int vb, bf16x8 pa0, bf16x8 pa1, bf16x8 pa2, bf16x8 pa3) {
;   const s16x4 l0 = tr_read<v_rd_off(D0, 0, 0)>(vb), h0 = tr_read<v_rd_off(D0, 0, 1)>(vb), l1 = tr_read<v_rd_off(D0, 1, 0)>(vb), h1 = tr_read<v_rd_off(D0, 1, 1)>(vb);
	v_mfma_f32_32x32x16_bf16 v[114:129], v[176:179], v[214:217], v[114:129]
	v_add_f32_e32 v255, v249, v255
	v_add_f32_e32 v255, v252, v255
	v_mfma_f32_32x32x16_bf16 v[82:97], v[180:183], v[214:217], v[82:97]
	v_add_u32_e32 v180, s2, v199
	ds_read_b128 v[176:179], v180
	ds_read_b128 v[180:183], v180 offset:4096
	ds_read_b128 v[214:217], v198 offset:2048
	v_add_f32_e32 v255, v253, v255
	v_add_f32_e32 v255, v254, v255
	s_waitcnt lgkmcnt(0)
	v_mfma_f32_32x32x16_bf16 v[114:129], v[176:179], v[214:217], v[114:129]
	v_add_f32_e32 v255, v108, v255
	v_add_f32_e32 v255, v109, v255
	v_mfma_f32_32x32x16_bf16 v[82:97], v[180:183], v[214:217], v[82:97]
	v_add_u32_e32 v180, s2, v202
	ds_read_b128 v[176:179], v180
	ds_read_b128 v[180:183], v180 offset:4096
	ds_read_b128 v[214:217], v198 offset:3072
	v_add_f32_e32 v255, v110, v255
	v_add_f32_e32 v255, v111, v255
	s_waitcnt lgkmcnt(0)
	v_mfma_f32_32x32x16_bf16 v[114:129], v[176:179], v[214:217], v[114:129]
	v_add_f32_e32 v255, v112, v255
	v_add_f32_e32 v255, v113, v255
	v_mfma_f32_32x32x16_bf16 v[82:97], v[180:183], v[214:217], v[82:97]
	v_cvt_pk_bf16_f32 v176, v253, v254
	v_cvt_pk_bf16_f32 v177, v108, v109
	v_cvt_pk_bf16_f32 v178, v110, v111
	v_cvt_pk_bf16_f32 v179, v112, v113
	v_cvt_pk_bf16_f32 v108, v98, v99
	v_cvt_pk_bf16_f32 v109, v238, v239
	v_cvt_pk_bf16_f32 v110, v246, v247
	v_cvt_pk_bf16_f32 v111, v249, v252
	v_mov_b32_e32 v98, v255
	v_add_u32_e32 v112, s11, v197
	ds_read_b64_tr_b16 v[180:181], v112 offset:0
	ds_read_b64_tr_b16 v[182:183], v112 offset:0x800
	ds_read_b64_tr_b16 v[214:215], v112 offset:0x1000
	ds_read_b64_tr_b16 v[216:217], v112 offset:0x1800
	ds_read_b64_tr_b16 v[218:219], v112 offset:0x2000
	ds_read_b64_tr_b16 v[220:221], v112 offset:0x2800
	ds_read_b64_tr_b16 v[222:223], v112 offset:0x3000
	ds_read_b64_tr_b16 v[224:225], v112 offset:0x3800
	s_waitcnt lgkmcnt(0)
	v_mov_b32_e32 v99, v98
	s_nop 1
	v_permlane32_swap_b32_e32 v98, v99
	v_permlane32_swap_b32_e32 v100, v102
	v_permlane32_swap_b32_e32 v176, v178
	v_permlane32_swap_b32_e32 v101, v103
	v_permlane32_swap_b32_e32 v104, v106
	v_permlane32_swap_b32_e32 v105, v107
	v_permlane32_swap_b32_e32 v108, v110
	v_permlane32_swap_b32_e32 v109, v111
	v_permlane32_swap_b32_e32 v177, v179
	v_mfma_f32_32x32x16_bf16 v[50:65], v[100:103], v[180:183], v[50:65]
	ds_read_b64_tr_b16 v[180:181], v112 offset:0x200
	ds_read_b64_tr_b16 v[182:183], v112 offset:0xa00
	v_mfma_f32_32x32x16_bf16 v[50:65], v[104:107], v[214:217], v[50:65]
	ds_read_b64_tr_b16 v[214:215], v112 offset:0x1200
	ds_read_b64_tr_b16 v[216:217], v112 offset:0x1a00
	v_mfma_f32_32x32x16_bf16 v[50:65], v[108:111], v[218:221], v[50:65]
	ds_read_b64_tr_b16 v[218:219], v112 offset:0x2200
	ds_read_b64_tr_b16 v[220:221], v112 offset:0x2a00
	v_mfma_f32_32x32x16_bf16 v[50:65], v[176:179], v[222:225], v[50:65]
	ds_read_b64_tr_b16 v[222:223], v112 offset:0x3200
	ds_read_b64_tr_b16 v[224:225], v112 offset:0x3a00
	s_waitcnt lgkmcnt(0)
	v_mfma_f32_32x32x16_bf16 v[34:49], v[100:103], v[180:183], v[34:49]
	ds_read_b64_tr_b16 v[180:181], v112 offset:0x400
	ds_read_b64_tr_b16 v[182:183], v112 offset:0xc00
	v_mfma_f32_32x32x16_bf16 v[34:49], v[104:107], v[214:217], v[34:49]
	ds_read_b64_tr_b16 v[214:215], v112 offset:0x1400
	ds_read_b64_tr_b16 v[216:217], v112 offset:0x1c00
	v_mfma_f32_32x32x16_bf16 v[34:49], v[108:111], v[218:221], v[34:49]
	ds_read_b64_tr_b16 v[218:219], v112 offset:0x2400
	ds_read_b64_tr_b16 v[220:221], v112 offset:0x2c00
	v_mfma_f32_32x32x16_bf16 v[34:49], v[176:179], v[222:225], v[34:49]
	ds_read_b64_tr_b16 v[222:223], v112 offset:0x3400
	ds_read_b64_tr_b16 v[224:225], v112 offset:0x3c00
	s_waitcnt lgkmcnt(0)
	v_mfma_f32_32x32x16_bf16 v[18:33], v[100:103], v[180:183], v[18:33]
	ds_read_b64_tr_b16 v[180:181], v112 offset:0x600
	ds_read_b64_tr_b16 v[182:183], v112 offset:0xe00
	v_mfma_f32_32x32x16_bf16 v[18:33], v[104:107], v[214:217], v[18:33]
	ds_read_b64_tr_b16 v[214:215], v112 offset:0x1600
	ds_read_b64_tr_b16 v[216:217], v112 offset:0x1e00
	v_mfma_f32_32x32x16_bf16 v[18:33], v[108:111], v[218:221], v[18:33]
	ds_read_b64_tr_b16 v[218:219], v112 offset:0x2600
	ds_read_b64_tr_b16 v[220:221], v112 offset:0x2e00
	v_mfma_f32_32x32x16_bf16 v[18:33], v[176:179], v[222:225], v[18:33]
	ds_read_b64_tr_b16 v[222:223], v112 offset:0x3600
	ds_read_b64_tr_b16 v[224:225], v112 offset:0x3e00
	s_waitcnt lgkmcnt(0)
	v_mfma_f32_32x32x16_bf16 v[2:17], v[100:103], v[180:183], v[2:17]
	v_max_f32_e32 v100, v115, v115
	v_max_f32_e32 v101, v114, v114
	v_max_f32_e32 v100, v101, v100
	v_max3_f32 v101, v116, v117, v83
	v_max3_f32 v100, v100, v82, v84
	v_max3_f32 v100, v100, v85, v118
	v_max3_f32 v101, v101, v120, v121
	v_mfma_f32_32x32x16_bf16 v[2:17], v[104:107], v[214:217], v[2:17]
	v_max3_f32 v100, v100, v119, v86
	v_max3_f32 v101, v101, v88, v89
	v_max3_f32 v100, v100, v87, v122
	v_max3_f32 v101, v101, v124, v125
	v_max3_f32 v100, v100, v123, v90
	v_max3_f32 v101, v101, v92, v93
	v_max3_f32 v100, v100, v91, v126
	v_mfma_f32_32x32x16_bf16 v[2:17], v[108:111], v[218:221], v[2:17]
	v_max3_f32 v101, v101, v128, v129
	v_max3_f32 v100, v100, v127, v94
	v_max3_f32 v101, v101, v96, v97
	v_max3_f32 v100, v100, v95, v101
	v_mov_b32_e32 v101, v100
	s_nop 1
	v_permlane32_swap_b32_e32 v100, v101
	v_mfma_f32_32x32x16_bf16 v[2:17], v[176:179], v[222:225], v[2:17]
	v_max_f32_e32 v101, v101, v101
	v_max_f32_e32 v100, v100, v100
	v_max_f32_e32 v100, v100, v101
	v_cmp_lt_f32_e32 vcc, s40, v100
	v_mov_b32_e32 v176, 1.0
	s_cbranch_vccnz .LBB0_114
	v_cmp_gt_f32_e32 vcc, 1.0, v176
	s_cbranch_vccz .LBB0_111
